# P0 weight copies (W1in, Win) rewritten by hand: 64x128 quad items, 32 x 16-byte loads in flight per wave, bf16-pair LDS transpose; adaLN workgroups copy nothing
# speedup vs baseline: 1.0081x; 1.0081x over previous
.LBB0_35:
	s_cmpk_lg_i32 s78, 0x100
	s_cbranch_scc1 .Lp0w_orig
	s_cmpk_lt_i32 s97, 0x90
	s_cbranch_scc1 .LBB0_149
	v_lshrrev_b32_e32 v1, 6, v236
	v_and_b32_e32 v2, 63, v236
	v_readfirstlane_b32 s0, v1
	v_and_b32_e32 v3, 31, v2
	v_lshrrev_b32_e32 v4, 5, v2
	s_nop 3
	s_sub_i32 s1, s97, 0x90
	s_lshl_b32 s1, s1, 3
	s_add_i32 s1, s1, s0
	s_lshl_b32 s2, s0, 14
	v_bfe_u32 v5, v3, 2, 1
	v_xor_b32_e32 v5, v5, v4
	v_lshlrev_b32_e32 v5, 6, v5
	v_lshl_or_b32 v5, v3, 9, v5
	v_add_u32_e32 v5, s2, v5
	v_and_b32_e32 v6, 3, v3
	v_xor_b32_e32 v7, 0, v6
	v_lshl_add_u32 v7, v7, 4, v5
	v_xor_b32_e32 v8, 1, v6
	v_lshl_add_u32 v8, v8, 4, v5
	v_xor_b32_e32 v9, 2, v6
	v_lshl_add_u32 v9, v9, 4, v5
	v_xor_b32_e32 v10, 3, v6
	v_lshl_add_u32 v10, v10, 4, v5
	v_and_b32_e32 v11, 7, v2
	v_xor_b32_e32 v11, v11, v4
	v_lshrrev_b32_e32 v12, 3, v2
	v_lshlrev_b32_e32 v12, 7, v12
	v_add_u32_e32 v12, s2, v12
	v_xor_b32_e32 v13, 0, v11
	v_lshl_add_u32 v13, v13, 4, v12
	v_xor_b32_e32 v14, 2, v11
	v_lshl_add_u32 v14, v14, 4, v12
	v_xor_b32_e32 v15, 4, v11
	v_lshl_add_u32 v15, v15, 4, v12
	v_xor_b32_e32 v16, 6, v11
	v_lshl_add_u32 v16, v16, 4, v12
	v_lshrrev_b32_e32 v17, 3, v2
	v_lshlrev_b32_e32 v17, 11, v17
	v_and_b32_e32 v18, 7, v2
	v_lshl_or_b32 v17, v18, 4, v17
	s_mov_b32 s3, 0
.Lp0w_round:
	s_cmpk_ge_u32 s1, 0x6e0
	s_cbranch_scc1 .Lp0w_done
	s_movk_i32 s9, 0x80
	s_cmpk_lt_u32 s1, 0x2c0
	s_cbranch_scc0 .Lp0w_win
	s_mul_i32 s4, s1, 0x5d2
	s_lshr_b32 s4, s4, 16
	s_mul_i32 s5, s4, 44
	s_sub_i32 s5, s1, s5
	s_and_b32 s6, s5, 1
	s_mul_i32 s6, s6, 0xb00
	s_lshr_b32 s7, s5, 1
	s_lshl_b32 s7, s7, 7
	s_add_i32 s6, s6, s7
	s_movk_i32 s8, 0x1600
	v_readlane_b32 s18, v246, 7
	v_readlane_b32 s19, v246, 8
	s_add_u32 s12, s74, 0x100000
	s_addc_u32 s13, s75, 0
	s_branch .Lp0w_go
.Lp0w_win:
	s_sub_i32 s14, s1, 0x2c0
	s_mul_i32 s4, s14, 0x3e1
	s_lshr_b32 s4, s4, 16
	s_mul_i32 s5, s4, 66
	s_sub_i32 s5, s14, s5
	s_movk_i32 s8, 0x2010
	v_readlane_b32 s18, v246, 13
	v_readlane_b32 s19, v246, 14
	s_add_u32 s12, s74, 0x1200000
	s_addc_u32 s13, s75, 0
	s_cmpk_lt_u32 s5, 24
	s_cbranch_scc0 .Lp0w_w1
	s_lshl_b32 s6, s5, 7
	s_branch .Lp0w_go
.Lp0w_w1:
	s_cmpk_lt_u32 s5, 32
	s_cbranch_scc0 .Lp0w_w2
	s_sub_i32 s6, s5, 24
	s_lshl_b32 s6, s6, 7
	s_add_i32 s6, s6, 0x1810
	s_branch .Lp0w_go
.Lp0w_w2:
	s_cmpk_lt_u32 s5, 48
	s_cbranch_scc0 .Lp0w_w3
	s_sub_i32 s7, s5, 32
	s_movk_i32 s6, 0xc10
	s_bitcmp1_b32 s7, 0
	s_cselect_b32 s6, 0x1c10, s6
	s_lshr_b32 s7, s7, 1
	s_lshl_b32 s7, s7, 7
	s_add_i32 s6, s6, s7
	s_branch .Lp0w_go
.Lp0w_w3:
	s_cmpk_lt_u32 s5, 64
	s_cbranch_scc0 .Lp0w_w4
	s_sub_i32 s7, s5, 48
	s_movk_i32 s6, 0x1010
	s_bitcmp1_b32 s7, 0
	s_cselect_b32 s6, 0x1410, s6
	s_lshr_b32 s7, s7, 1
	s_lshl_b32 s7, s7, 7
	s_add_i32 s6, s6, s7
	s_branch .Lp0w_go
.Lp0w_w4:
	s_movk_i32 s6, 0xc00
	s_movk_i32 s9, 16
	s_cmpk_eq_u32 s5, 64
	s_cbranch_scc1 .Lp0w_go
	s_mov_b32 s6, 0
	s_mov_b32 s9, 0
.Lp0w_go:
	s_lshl_b32 s14, s4, 6
	s_mul_i32 s14, s14, s8
	s_add_i32 s14, s14, s6
	s_lshl_b32 s14, s14, 2
	s_add_u32 s18, s18, s14
	s_addc_u32 s19, s19, 0
	s_lshl_b32 s15, s8, 2
	s_lshl_b32 s16, s8, 7
	v_mul_u32_u24_e32 v19, s16, v4
	v_lshl_add_u32 v19, v3, 4, v19
	s_lshr_b32 s17, s9, 2
	s_cmpk_eq_u32 s9, 0x80
	s_cbranch_scc1 .Lp0w_nozero
	v_mov_b32_e32 v20, 0
	v_mov_b32_e32 v21, 0
	v_mov_b32_e32 v22, 0
	v_mov_b32_e32 v23, 0
	v_mov_b32_e32 v24, 0
	v_mov_b32_e32 v25, 0
	v_mov_b32_e32 v26, 0
	v_mov_b32_e32 v27, 0
	v_mov_b32_e32 v28, 0
	v_mov_b32_e32 v29, 0
	v_mov_b32_e32 v30, 0
	v_mov_b32_e32 v31, 0
	v_mov_b32_e32 v32, 0
	v_mov_b32_e32 v33, 0
	v_mov_b32_e32 v34, 0
	v_mov_b32_e32 v35, 0
	v_mov_b32_e32 v36, 0
	v_mov_b32_e32 v37, 0
	v_mov_b32_e32 v38, 0
	v_mov_b32_e32 v39, 0
	v_mov_b32_e32 v40, 0
	v_mov_b32_e32 v41, 0
	v_mov_b32_e32 v42, 0
	v_mov_b32_e32 v43, 0
	v_mov_b32_e32 v44, 0
	v_mov_b32_e32 v45, 0
	v_mov_b32_e32 v46, 0
	v_mov_b32_e32 v47, 0
	v_mov_b32_e32 v48, 0
	v_mov_b32_e32 v49, 0
	v_mov_b32_e32 v50, 0
	v_mov_b32_e32 v51, 0
	v_mov_b32_e32 v52, 0
	v_mov_b32_e32 v53, 0
	v_mov_b32_e32 v54, 0
	v_mov_b32_e32 v55, 0
	v_mov_b32_e32 v56, 0
	v_mov_b32_e32 v57, 0
	v_mov_b32_e32 v58, 0
	v_mov_b32_e32 v59, 0
	v_mov_b32_e32 v60, 0
	v_mov_b32_e32 v61, 0
	v_mov_b32_e32 v62, 0
	v_mov_b32_e32 v63, 0
	v_mov_b32_e32 v64, 0
	v_mov_b32_e32 v65, 0
	v_mov_b32_e32 v66, 0
	v_mov_b32_e32 v67, 0
	v_mov_b32_e32 v68, 0
	v_mov_b32_e32 v69, 0
	v_mov_b32_e32 v70, 0
	v_mov_b32_e32 v71, 0
	v_mov_b32_e32 v76, 0
	v_mov_b32_e32 v77, 0
	v_mov_b32_e32 v78, 0
	v_mov_b32_e32 v79, 0
	v_mov_b32_e32 v80, 0
	v_mov_b32_e32 v81, 0
	v_mov_b32_e32 v82, 0
	v_mov_b32_e32 v83, 0
	v_mov_b32_e32 v84, 0
	v_mov_b32_e32 v85, 0
	v_mov_b32_e32 v86, 0
	v_mov_b32_e32 v87, 0
	v_mov_b32_e32 v88, 0
	v_mov_b32_e32 v89, 0
	v_mov_b32_e32 v90, 0
	v_mov_b32_e32 v91, 0
	v_mov_b32_e32 v92, 0
	v_mov_b32_e32 v93, 0
	v_mov_b32_e32 v94, 0
	v_mov_b32_e32 v95, 0
	v_mov_b32_e32 v108, 0
	v_mov_b32_e32 v109, 0
	v_mov_b32_e32 v110, 0
	v_mov_b32_e32 v111, 0
	v_mov_b32_e32 v112, 0
	v_mov_b32_e32 v113, 0
	v_mov_b32_e32 v114, 0
	v_mov_b32_e32 v115, 0
	v_mov_b32_e32 v116, 0
	v_mov_b32_e32 v117, 0
	v_mov_b32_e32 v118, 0
	v_mov_b32_e32 v119, 0
	v_mov_b32_e32 v120, 0
	v_mov_b32_e32 v121, 0
	v_mov_b32_e32 v122, 0
	v_mov_b32_e32 v123, 0
	v_mov_b32_e32 v124, 0
	v_mov_b32_e32 v125, 0
	v_mov_b32_e32 v126, 0
	v_mov_b32_e32 v127, 0
	v_mov_b32_e32 v128, 0
	v_mov_b32_e32 v129, 0
	v_mov_b32_e32 v130, 0
	v_mov_b32_e32 v131, 0
	v_mov_b32_e32 v132, 0
	v_mov_b32_e32 v133, 0
	v_mov_b32_e32 v134, 0
	v_mov_b32_e32 v135, 0
	v_mov_b32_e32 v136, 0
	v_mov_b32_e32 v137, 0
	v_mov_b32_e32 v138, 0
	v_mov_b32_e32 v139, 0
	v_mov_b32_e32 v140, 0
	v_mov_b32_e32 v141, 0
	v_mov_b32_e32 v142, 0
	v_mov_b32_e32 v143, 0
	v_mov_b32_e32 v144, 0
	v_mov_b32_e32 v145, 0
	v_mov_b32_e32 v146, 0
	v_mov_b32_e32 v147, 0
	v_mov_b32_e32 v148, 0
	v_mov_b32_e32 v149, 0
	v_mov_b32_e32 v150, 0
	v_mov_b32_e32 v151, 0
	v_mov_b32_e32 v152, 0
	v_mov_b32_e32 v153, 0
	v_mov_b32_e32 v154, 0
	v_mov_b32_e32 v155, 0
	v_mov_b32_e32 v156, 0
	v_mov_b32_e32 v157, 0
	v_mov_b32_e32 v158, 0
	v_mov_b32_e32 v159, 0
	v_mov_b32_e32 v160, 0
	v_mov_b32_e32 v161, 0
	v_mov_b32_e32 v162, 0
	v_mov_b32_e32 v163, 0
.Lp0w_nozero:
	s_mov_b64 s[20:21], exec
	v_cmp_gt_u32_e32 vcc, s17, v3
	s_and_b64 exec, exec, vcc
	global_load_dwordx4 v[20:23], v19, s[18:19] nt
	s_add_u32 s18, s18, s15
	s_addc_u32 s19, s19, 0
	global_load_dwordx4 v[24:27], v19, s[18:19] nt
	s_add_u32 s18, s18, s15
	s_addc_u32 s19, s19, 0
	global_load_dwordx4 v[28:31], v19, s[18:19] nt
	s_add_u32 s18, s18, s15
	s_addc_u32 s19, s19, 0
	global_load_dwordx4 v[32:35], v19, s[18:19] nt
	s_add_u32 s18, s18, s15
	s_addc_u32 s19, s19, 0
	global_load_dwordx4 v[36:39], v19, s[18:19] nt
	s_add_u32 s18, s18, s15
	s_addc_u32 s19, s19, 0
	global_load_dwordx4 v[40:43], v19, s[18:19] nt
	s_add_u32 s18, s18, s15
	s_addc_u32 s19, s19, 0
	global_load_dwordx4 v[44:47], v19, s[18:19] nt
	s_add_u32 s18, s18, s15
	s_addc_u32 s19, s19, 0
	global_load_dwordx4 v[48:51], v19, s[18:19] nt
	s_add_u32 s18, s18, s15
	s_addc_u32 s19, s19, 0
	global_load_dwordx4 v[52:55], v19, s[18:19] nt
	s_add_u32 s18, s18, s15
	s_addc_u32 s19, s19, 0
	global_load_dwordx4 v[56:59], v19, s[18:19] nt
	s_add_u32 s18, s18, s15
	s_addc_u32 s19, s19, 0
	global_load_dwordx4 v[60:63], v19, s[18:19] nt
	s_add_u32 s18, s18, s15
	s_addc_u32 s19, s19, 0
	global_load_dwordx4 v[64:67], v19, s[18:19] nt
	s_add_u32 s18, s18, s15
	s_addc_u32 s19, s19, 0
	global_load_dwordx4 v[68:71], v19, s[18:19] nt
	s_add_u32 s18, s18, s15
	s_addc_u32 s19, s19, 0
	global_load_dwordx4 v[76:79], v19, s[18:19] nt
	s_add_u32 s18, s18, s15
	s_addc_u32 s19, s19, 0
	global_load_dwordx4 v[80:83], v19, s[18:19] nt
	s_add_u32 s18, s18, s15
	s_addc_u32 s19, s19, 0
	global_load_dwordx4 v[84:87], v19, s[18:19] nt
	s_add_u32 s18, s18, s15
	s_addc_u32 s19, s19, 0
	global_load_dwordx4 v[88:91], v19, s[18:19] nt
	s_add_u32 s18, s18, s15
	s_addc_u32 s19, s19, 0
	global_load_dwordx4 v[92:95], v19, s[18:19] nt
	s_add_u32 s18, s18, s15
	s_addc_u32 s19, s19, 0
	global_load_dwordx4 v[108:111], v19, s[18:19] nt
	s_add_u32 s18, s18, s15
	s_addc_u32 s19, s19, 0
	global_load_dwordx4 v[112:115], v19, s[18:19] nt
	s_add_u32 s18, s18, s15
	s_addc_u32 s19, s19, 0
	global_load_dwordx4 v[116:119], v19, s[18:19] nt
	s_add_u32 s18, s18, s15
	s_addc_u32 s19, s19, 0
	global_load_dwordx4 v[120:123], v19, s[18:19] nt
	s_add_u32 s18, s18, s15
	s_addc_u32 s19, s19, 0
	global_load_dwordx4 v[124:127], v19, s[18:19] nt
	s_add_u32 s18, s18, s15
	s_addc_u32 s19, s19, 0
	global_load_dwordx4 v[128:131], v19, s[18:19] nt
	s_add_u32 s18, s18, s15
	s_addc_u32 s19, s19, 0
	global_load_dwordx4 v[132:135], v19, s[18:19] nt
	s_add_u32 s18, s18, s15
	s_addc_u32 s19, s19, 0
	global_load_dwordx4 v[136:139], v19, s[18:19] nt
	s_add_u32 s18, s18, s15
	s_addc_u32 s19, s19, 0
	global_load_dwordx4 v[140:143], v19, s[18:19] nt
	s_add_u32 s18, s18, s15
	s_addc_u32 s19, s19, 0
	global_load_dwordx4 v[144:147], v19, s[18:19] nt
	s_add_u32 s18, s18, s15
	s_addc_u32 s19, s19, 0
	global_load_dwordx4 v[148:151], v19, s[18:19] nt
	s_add_u32 s18, s18, s15
	s_addc_u32 s19, s19, 0
	global_load_dwordx4 v[152:155], v19, s[18:19] nt
	s_add_u32 s18, s18, s15
	s_addc_u32 s19, s19, 0
	global_load_dwordx4 v[156:159], v19, s[18:19] nt
	s_add_u32 s18, s18, s15
	s_addc_u32 s19, s19, 0
	global_load_dwordx4 v[160:163], v19, s[18:19] nt
	s_mov_b64 exec, s[20:21]
	s_lshl_b32 s14, s5, 18
	s_lshl_b32 s22, s4, 7
	s_add_i32 s14, s14, s22
	s_add_u32 s22, s12, s14
	s_addc_u32 s23, s13, 0
	s_waitcnt vmcnt(0)
	v_cvt_pk_bf16_f32 v20, v20, v24
	v_cvt_pk_bf16_f32 v21, v21, v25
	v_cvt_pk_bf16_f32 v22, v22, v26
	v_cvt_pk_bf16_f32 v23, v23, v27
	v_cvt_pk_bf16_f32 v28, v28, v32
	v_cvt_pk_bf16_f32 v29, v29, v33
	v_cvt_pk_bf16_f32 v30, v30, v34
	v_cvt_pk_bf16_f32 v31, v31, v35
	v_cvt_pk_bf16_f32 v36, v36, v40
	v_cvt_pk_bf16_f32 v37, v37, v41
	v_cvt_pk_bf16_f32 v38, v38, v42
	v_cvt_pk_bf16_f32 v39, v39, v43
	v_cvt_pk_bf16_f32 v44, v44, v48
	v_cvt_pk_bf16_f32 v45, v45, v49
	v_cvt_pk_bf16_f32 v46, v46, v50
	v_cvt_pk_bf16_f32 v47, v47, v51
	v_cvt_pk_bf16_f32 v52, v52, v56
	v_cvt_pk_bf16_f32 v53, v53, v57
	v_cvt_pk_bf16_f32 v54, v54, v58
	v_cvt_pk_bf16_f32 v55, v55, v59
	v_cvt_pk_bf16_f32 v60, v60, v64
	v_cvt_pk_bf16_f32 v61, v61, v65
	v_cvt_pk_bf16_f32 v62, v62, v66
	v_cvt_pk_bf16_f32 v63, v63, v67
	v_cvt_pk_bf16_f32 v68, v68, v76
	v_cvt_pk_bf16_f32 v69, v69, v77
	v_cvt_pk_bf16_f32 v70, v70, v78
	v_cvt_pk_bf16_f32 v71, v71, v79
	v_cvt_pk_bf16_f32 v80, v80, v84
	v_cvt_pk_bf16_f32 v81, v81, v85
	v_cvt_pk_bf16_f32 v82, v82, v86
	v_cvt_pk_bf16_f32 v83, v83, v87
	v_cvt_pk_bf16_f32 v88, v88, v92
	v_cvt_pk_bf16_f32 v89, v89, v93
	v_cvt_pk_bf16_f32 v90, v90, v94
	v_cvt_pk_bf16_f32 v91, v91, v95
	v_cvt_pk_bf16_f32 v108, v108, v112
	v_cvt_pk_bf16_f32 v109, v109, v113
	v_cvt_pk_bf16_f32 v110, v110, v114
	v_cvt_pk_bf16_f32 v111, v111, v115
	v_cvt_pk_bf16_f32 v116, v116, v120
	v_cvt_pk_bf16_f32 v117, v117, v121
	v_cvt_pk_bf16_f32 v118, v118, v122
	v_cvt_pk_bf16_f32 v119, v119, v123
	v_cvt_pk_bf16_f32 v124, v124, v128
	v_cvt_pk_bf16_f32 v125, v125, v129
	v_cvt_pk_bf16_f32 v126, v126, v130
	v_cvt_pk_bf16_f32 v127, v127, v131
	v_cvt_pk_bf16_f32 v132, v132, v136
	v_cvt_pk_bf16_f32 v133, v133, v137
	v_cvt_pk_bf16_f32 v134, v134, v138
	v_cvt_pk_bf16_f32 v135, v135, v139
	v_cvt_pk_bf16_f32 v140, v140, v144
	v_cvt_pk_bf16_f32 v141, v141, v145
	v_cvt_pk_bf16_f32 v142, v142, v146
	v_cvt_pk_bf16_f32 v143, v143, v147
	v_cvt_pk_bf16_f32 v148, v148, v152
	v_cvt_pk_bf16_f32 v149, v149, v153
	v_cvt_pk_bf16_f32 v150, v150, v154
	v_cvt_pk_bf16_f32 v151, v151, v155
	v_cvt_pk_bf16_f32 v156, v156, v160
	v_cvt_pk_bf16_f32 v157, v157, v161
	v_cvt_pk_bf16_f32 v158, v158, v162
	v_cvt_pk_bf16_f32 v159, v159, v163
	ds_write_b32 v7, v20
	ds_write_b32 v7, v21 offset:128
	ds_write_b32 v7, v22 offset:256
	ds_write_b32 v7, v23 offset:384
	ds_write_b32 v7, v28 offset:4
	ds_write_b32 v7, v29 offset:132
	ds_write_b32 v7, v30 offset:260
	ds_write_b32 v7, v31 offset:388
	ds_write_b32 v7, v36 offset:8
	ds_write_b32 v7, v37 offset:136
	ds_write_b32 v7, v38 offset:264
	ds_write_b32 v7, v39 offset:392
	ds_write_b32 v7, v44 offset:12
	ds_write_b32 v7, v45 offset:140
	ds_write_b32 v7, v46 offset:268
	ds_write_b32 v7, v47 offset:396
	ds_write_b32 v8, v52
	ds_write_b32 v8, v53 offset:128
	ds_write_b32 v8, v54 offset:256
	ds_write_b32 v8, v55 offset:384
	ds_write_b32 v8, v60 offset:4
	ds_write_b32 v8, v61 offset:132
	ds_write_b32 v8, v62 offset:260
	ds_write_b32 v8, v63 offset:388
	ds_write_b32 v8, v68 offset:8
	ds_write_b32 v8, v69 offset:136
	ds_write_b32 v8, v70 offset:264
	ds_write_b32 v8, v71 offset:392
	ds_write_b32 v8, v80 offset:12
	ds_write_b32 v8, v81 offset:140
	ds_write_b32 v8, v82 offset:268
	ds_write_b32 v8, v83 offset:396
	ds_write_b32 v9, v88
	ds_write_b32 v9, v89 offset:128
	ds_write_b32 v9, v90 offset:256
	ds_write_b32 v9, v91 offset:384
	ds_write_b32 v9, v108 offset:4
	ds_write_b32 v9, v109 offset:132
	ds_write_b32 v9, v110 offset:260
	ds_write_b32 v9, v111 offset:388
	ds_write_b32 v9, v116 offset:8
	ds_write_b32 v9, v117 offset:136
	ds_write_b32 v9, v118 offset:264
	ds_write_b32 v9, v119 offset:392
	ds_write_b32 v9, v124 offset:12
	ds_write_b32 v9, v125 offset:140
	ds_write_b32 v9, v126 offset:268
	ds_write_b32 v9, v127 offset:396
	ds_write_b32 v10, v132
	ds_write_b32 v10, v133 offset:128
	ds_write_b32 v10, v134 offset:256
	ds_write_b32 v10, v135 offset:384
	ds_write_b32 v10, v140 offset:4
	ds_write_b32 v10, v141 offset:132
	ds_write_b32 v10, v142 offset:260
	ds_write_b32 v10, v143 offset:388
	ds_write_b32 v10, v148 offset:8
	ds_write_b32 v10, v149 offset:136
	ds_write_b32 v10, v150 offset:264
	ds_write_b32 v10, v151 offset:392
	ds_write_b32 v10, v156 offset:12
	ds_write_b32 v10, v157 offset:140
	ds_write_b32 v10, v158 offset:268
	ds_write_b32 v10, v159 offset:396
	s_waitcnt lgkmcnt(0)
	ds_read_b128 v[24:27], v13
	ds_read_b128 v[32:35], v14 offset:1024
	ds_read_b128 v[40:43], v15 offset:2048
	ds_read_b128 v[48:51], v16 offset:3072
	ds_read_b128 v[56:59], v13 offset:4096
	ds_read_b128 v[64:67], v14 offset:5120
	ds_read_b128 v[76:79], v15 offset:6144
	ds_read_b128 v[84:87], v16 offset:7168
	ds_read_b128 v[92:95], v13 offset:8192
	ds_read_b128 v[112:115], v14 offset:9216
	ds_read_b128 v[120:123], v15 offset:10240
	ds_read_b128 v[128:131], v16 offset:11264
	ds_read_b128 v[136:139], v13 offset:12288
	ds_read_b128 v[144:147], v14 offset:13312
	ds_read_b128 v[152:155], v15 offset:14336
	ds_read_b128 v[160:163], v16 offset:15360
	s_waitcnt lgkmcnt(15)
	global_store_dwordx4 v17, v[24:27], s[22:23]
	s_add_u32 s22, s22, 0x4000
	s_addc_u32 s23, s23, 0
	s_waitcnt lgkmcnt(14)
	global_store_dwordx4 v17, v[32:35], s[22:23]
	s_add_u32 s22, s22, 0x4000
	s_addc_u32 s23, s23, 0
	s_waitcnt lgkmcnt(13)
	global_store_dwordx4 v17, v[40:43], s[22:23]
	s_add_u32 s22, s22, 0x4000
	s_addc_u32 s23, s23, 0
	s_waitcnt lgkmcnt(12)
	global_store_dwordx4 v17, v[48:51], s[22:23]
	s_add_u32 s22, s22, 0x4000
	s_addc_u32 s23, s23, 0
	s_waitcnt lgkmcnt(11)
	global_store_dwordx4 v17, v[56:59], s[22:23]
	s_add_u32 s22, s22, 0x4000
	s_addc_u32 s23, s23, 0
	s_waitcnt lgkmcnt(10)
	global_store_dwordx4 v17, v[64:67], s[22:23]
	s_add_u32 s22, s22, 0x4000
	s_addc_u32 s23, s23, 0
	s_waitcnt lgkmcnt(9)
	global_store_dwordx4 v17, v[76:79], s[22:23]
	s_add_u32 s22, s22, 0x4000
	s_addc_u32 s23, s23, 0
	s_waitcnt lgkmcnt(8)
	global_store_dwordx4 v17, v[84:87], s[22:23]
	s_add_u32 s22, s22, 0x4000
	s_addc_u32 s23, s23, 0
	s_waitcnt lgkmcnt(7)
	global_store_dwordx4 v17, v[92:95], s[22:23]
	s_add_u32 s22, s22, 0x4000
	s_addc_u32 s23, s23, 0
	s_waitcnt lgkmcnt(6)
	global_store_dwordx4 v17, v[112:115], s[22:23]
	s_add_u32 s22, s22, 0x4000
	s_addc_u32 s23, s23, 0
	s_waitcnt lgkmcnt(5)
	global_store_dwordx4 v17, v[120:123], s[22:23]
	s_add_u32 s22, s22, 0x4000
	s_addc_u32 s23, s23, 0
	s_waitcnt lgkmcnt(4)
	global_store_dwordx4 v17, v[128:131], s[22:23]
	s_add_u32 s22, s22, 0x4000
	s_addc_u32 s23, s23, 0
	s_waitcnt lgkmcnt(3)
	global_store_dwordx4 v17, v[136:139], s[22:23]
	s_add_u32 s22, s22, 0x4000
	s_addc_u32 s23, s23, 0
	s_waitcnt lgkmcnt(2)
	global_store_dwordx4 v17, v[144:147], s[22:23]
	s_add_u32 s22, s22, 0x4000
	s_addc_u32 s23, s23, 0
	s_waitcnt lgkmcnt(1)
	global_store_dwordx4 v17, v[152:155], s[22:23]
	s_add_u32 s22, s22, 0x4000
	s_addc_u32 s23, s23, 0
	s_waitcnt lgkmcnt(0)
	global_store_dwordx4 v17, v[160:163], s[22:23]
	s_addk_i32 s1, 0x380
	s_add_i32 s3, s3, 1
	s_cmp_lt_u32 s3, 2
	s_cbranch_scc1 .Lp0w_round
.Lp0w_done:
	s_branch .LBB0_149

.LBB0_227:
	s_cmp_lt_i32 s76, 3
	s_cselect_b64 s[0:1], -1, 0
	s_add_u32 s80, s74, 0x5800000
	s_addc_u32 s81, s75, 0
	s_and_b64 s[0:1], s[0:1], s[2:3]
	s_andn2_b64 vcc, exec, s[0:1]
	s_cbranch_vccnz .LBB0_249
	s_cmpk_gt_i32 s96, 0x5d7
	v_readfirstlane_b32 s3, v236
	s_cbranch_scc1 .LBB0_244
	v_lshrrev_b32_e32 v0, 5, v236
	v_lshrrev_b32_e32 v2, 1, v236
	v_and_b32_e32 v0, 4, v0
	v_bfe_u32 v1, v236, 2, 2
	v_and_b32_e32 v11, 24, v2
	v_or3_b32 v0, v0, v1, v11
	v_lshlrev_b32_e32 v1, 4, v236
	v_add_u32_e32 v8, 0x2000, v1
	v_lshrrev_b32_e32 v2, 7, v8
	s_movk_i32 s2, 0xe0
	v_and_b32_e32 v4, 32, v236
	v_and_or_b32 v3, v2, s2, v0
	v_bitop3_b32 v9, v1, v4, 48 bitop3:0x6c
	v_and_b32_e32 v10, 64, v236
	v_bfe_u32 v12, v236, 2, 4
	s_movk_i32 s2, 0xf0
	v_or_b32_e32 v1, v9, v10
	v_and_or_b32 v2, v2, s2, v12
	s_add_u32 s26, s74, 0x100000
	v_lshl_or_b32 v130, v2, 11, v1
	v_lshrrev_b32_e32 v2, 3, v236
	s_movk_i32 s2, 0x60
	s_addc_u32 s27, s75, 0
	v_and_or_b32 v0, v2, s2, v0
	s_movk_i32 s2, 0x70
	s_ashr_i32 s29, s96, 31
	v_lshl_or_b32 v132, v0, 11, v1
	v_and_or_b32 v0, v2, s2, v12
	s_lshr_b32 s2, s29, 29
	s_add_i32 s2, s96, s2
	s_lshr_b32 s6, s3, 6
	s_ashr_i32 s4, s2, 3
	s_and_b32 s2, s2, -8
	s_lshr_b32 s8, s3, 8
	s_lshl_b32 s28, s6, 10
	s_sub_i32 s2, s96, s2
	s_cmp_lt_i32 s2, 0
	s_movk_i32 s30, 0xbc
	s_cselect_b32 s5, s30, 0xbb
	s_mul_i32 s2, s2, s5
	s_add_i32 s2, s2, s4
	s_mul_hi_i32 s4, s2, 0x2e8ba2e9
	s_lshr_b32 s5, s4, 31
	s_ashr_i32 s4, s4, 5
	s_add_i32 s4, s4, s5
	s_lshl_b32 s7, s4, 3
	s_sub_i32 s5, 0x44, s7
	s_mulk_i32 s4, 0xb0
	s_min_u32 s9, s5, 8
	s_sub_i32 s10, s2, s4
	v_lshl_or_b32 v128, v3, 11, v1
	s_sext_i32_i16 s2, s10
	v_cvt_f32_ubyte0_e32 v3, s9
	v_cvt_f32_i32_e32 v2, s2
	v_rcp_iflag_f32_e32 v4, v3
	v_lshl_or_b32 v134, v0, 11, v1
	s_ashr_i32 s2, s2, 30
	s_or_b32 s2, s2, 1
	v_mul_f32_e32 v0, v2, v4
	v_trunc_f32_e32 v0, v0
	v_fma_f32 v1, -v0, v3, v2
	v_cvt_i32_f32_e32 v0, v0
	v_cmp_ge_f32_e64 s[4:5], |v1|, v3
	s_and_b64 s[4:5], s[4:5], exec
	s_cselect_b32 s2, s2, 0
	v_readfirstlane_b32 s4, v0
	s_add_i32 s2, s4, s2
	s_mul_i32 s4, s2, s9
	s_sub_i32 s4, s10, s4
	s_sext_i32_i16 s4, s4
	s_add_i32 s18, s7, s4
	s_ashr_i32 s19, s18, 31
	s_bfe_i64 s[10:11], s[2:3], 0x100000
	s_lshl_b64 s[4:5], s[18:19], 19
	s_lshl_b64 s[10:11], s[10:11], 19
	s_add_u32 s22, s26, s10
	s_addc_u32 s23, s27, s11
	s_add_i32 s19, s28, 0
	s_add_i32 m0, s19, 0x10000
	v_mov_b32_e32 v133, 0
	global_load_lds_dwordx4 v132, s[22:23]
	s_add_i32 m0, s19, 0x12000
	s_add_u32 s10, s22, 0x40000
	global_load_lds_dwordx4 v128, s[22:23]
	s_addc_u32 s11, s23, 0
	s_add_i32 m0, s19, 0x14000
	v_mov_b32_e32 v129, v133
	global_load_lds_dwordx4 v132, s[10:11]
	s_add_i32 m0, s19, 0x16000
	v_mov_b32_e32 v135, v133
	global_load_lds_dwordx4 v128, s[10:11]
	v_readlane_b32 s10, v246, 42
	v_readlane_b32 s11, v246, 43
	s_add_u32 s20, s10, s4
	s_addc_u32 s21, s11, s5
	s_add_i32 s31, s19, 0x2000
	s_mov_b32 m0, s19
	s_add_u32 s4, s20, 0x40000
	global_load_lds_dwordx4 v134, s[20:21]
	s_mov_b32 m0, s31
	s_addc_u32 s5, s21, 0
	s_add_i32 s33, s19, 0x4000
	global_load_lds_dwordx4 v130, s[20:21]
	s_mov_b32 m0, s33
	s_add_i32 s34, s19, 0x6000
	global_load_lds_dwordx4 v134, s[4:5]
	s_mov_b32 m0, s34
	v_mov_b32_e32 v131, v133
	global_load_lds_dwordx4 v130, s[4:5]
	s_cmp_eq_u32 s8, 1
	s_mov_b32 s35, 0
	v_lshl_add_u64 v[6:7], s[22:23], 0, v[132:133]
	v_lshl_add_u64 v[4:5], s[22:23], 0, v[128:129]
	v_lshl_add_u64 v[0:1], s[20:21], 0, v[134:135]
	s_cselect_b64 s[4:5], -1, 0
	s_cmp_lg_u32 s8, 1
	v_lshl_add_u64 v[2:3], s[20:21], 0, v[130:131]
	s_cbranch_scc1 .LBB0_231
	s_barrier
.LBB0_231:
	s_lshl_b32 s6, s6, 5
	s_and_b32 s12, s6, 0x60
	s_mov_b64 s[6:7], 0x80
	s_add_i32 m0, s19, 0x18000
	v_lshl_add_u64 v[6:7], v[6:7], 0, s[6:7]
	s_lshl_b32 s9, s8, 13
	s_lshl_b32 s13, s12, 7
	s_waitcnt vmcnt(2)
	s_barrier
	global_load_lds_dwordx4 v[6:7], off
	v_lshl_add_u64 v[4:5], v[4:5], 0, s[6:7]
	s_add_i32 m0, s19, 0x1a000
	s_add_i32 s36, s19, 0x8000
	s_add_i32 s37, s19, 0xa000
	global_load_lds_dwordx4 v[4:5], off
	v_lshl_add_u64 v[0:1], v[0:1], 0, s[6:7]
	s_mov_b32 m0, s36
	s_add_u32 s10, s22, 0x40080
	global_load_lds_dwordx4 v[0:1], off
	v_lshl_add_u64 v[0:1], v[2:3], 0, s[6:7]
	s_mov_b32 m0, s37
	s_addc_u32 s11, s23, 0
	global_load_lds_dwordx4 v[0:1], off
	s_add_i32 m0, s19, 0x1c000
	v_lshl_add_u64 v[0:1], s[10:11], 0, v[132:133]
	global_load_lds_dwordx4 v[0:1], off
	v_lshl_add_u64 v[0:1], s[10:11], 0, v[128:129]
	s_add_i32 m0, s19, 0x1e000
	s_sext_i32_i16 s43, s2
	global_load_lds_dwordx4 v[0:1], off
	v_and_b32_e32 v0, 15, v236
	v_lshlrev_b32_e32 v1, 1, v11
	v_lshlrev_b32_e32 v2, 2, v236
	v_lshlrev_b32_e32 v3, 6, v236
	s_movk_i32 s2, 0x3c0
	v_lshl_or_b32 v144, s8, 6, v0
	v_lshl_or_b32 v0, v0, 6, v1
	v_and_b32_e32 v2, 32, v2
	v_and_or_b32 v1, v3, s2, v1
	v_bitop3_b32 v145, s13, v1, v2 bitop3:0xf6
	v_lshlrev_b32_e32 v1, 8, v236
	v_bitop3_b32 v0, v0, s9, v2 bitop3:0xde
	v_and_b32_e32 v1, 0x38000, v1
	v_lshlrev_b32_e32 v2, 11, v12
	v_or3_b32 v1, v9, v1, v2
	v_add_u32_e32 v136, v1, v10
	v_lshlrev_b32_e32 v1, 4, v8
	s_waitcnt vmcnt(6)
	s_cmpk_lt_u32 s3, 0x100
	v_and_b32_e32 v1, 0x78000, v1
	s_cselect_b64 s[8:9], -1, 0
	v_or3_b32 v1, v9, v1, v2
	s_add_i32 s40, 0, 0x10000
	s_add_i32 s41, 0, 0x14000
	s_ashr_i32 s38, s78, 31
	s_mov_b32 s39, s78
	v_or_b32_e32 v146, s12, v11
	v_mov_b32_e32 v137, v133
	v_add_u32_e32 v138, v1, v10
	v_mov_b32_e32 v139, v133
	v_mov_b64_e32 v[140:141], 0x5d8
	v_mov_b64_e32 v[142:143], 0x5d7
	v_add_u32_e32 v147, s40, v145
	v_add_u32_e32 v148, s41, v145
	v_add_u32_e32 v149, 0, v0
	s_movk_i32 s42, 0x1600
	s_barrier
	s_branch .LBB0_234

.LBB0_236:
	s_ashr_i32 s13, s12, 31
	s_lshl_b64 s[14:15], s[12:13], 19
	v_readlane_b32 s16, v246, 42
	v_readlane_b32 s17, v246, 43
	s_add_u32 s14, s16, s14
	s_addc_u32 s15, s17, s15
	s_and_b64 s[16:17], s[2:3], exec
	s_cselect_b32 s13, s15, s21
	s_cselect_b32 s44, s14, s20
	s_ashr_i32 s11, s10, 31
	s_lshl_b64 s[16:17], s[10:11], 19
	s_add_u32 s16, s26, s16
	s_addc_u32 s17, s27, s17
	s_and_b64 s[24:25], s[2:3], exec
	s_cselect_b32 s11, s17, s23
	s_cselect_b32 s45, s16, s22
	s_add_u32 s20, s20, 0x40080
	s_addc_u32 s21, s21, 0
	s_add_u32 s46, s22, 0x100
	v_mov_b32_e32 v0, 0
	s_addc_u32 s47, s23, 0
	s_mov_b32 s48, -2
	v_mov_b32_e32 v1, v0
	v_mov_b32_e32 v2, v0
	v_mov_b32_e32 v3, v0
	v_mov_b32_e32 v4, v0
	v_mov_b32_e32 v5, v0
	v_mov_b32_e32 v6, v0
	v_mov_b32_e32 v7, v0
	v_mov_b32_e32 v16, v0
	v_mov_b32_e32 v17, v0
	v_mov_b32_e32 v18, v0
	v_mov_b32_e32 v19, v0
	v_mov_b32_e32 v20, v0
	v_mov_b32_e32 v21, v0
	v_mov_b32_e32 v22, v0
	v_mov_b32_e32 v23, v0
	v_mov_b32_e32 v32, v0
	v_mov_b32_e32 v33, v0
	v_mov_b32_e32 v34, v0
	v_mov_b32_e32 v35, v0
	v_mov_b32_e32 v36, v0
	v_mov_b32_e32 v37, v0
	v_mov_b32_e32 v38, v0
	v_mov_b32_e32 v39, v0
	v_mov_b32_e32 v48, v0
	v_mov_b32_e32 v49, v0
	v_mov_b32_e32 v50, v0
	v_mov_b32_e32 v51, v0
	v_mov_b32_e32 v52, v0
	v_mov_b32_e32 v53, v0
	v_mov_b32_e32 v54, v0
	v_mov_b32_e32 v55, v0
	v_mov_b32_e32 v8, v0
	v_mov_b32_e32 v9, v0
	v_mov_b32_e32 v10, v0
	v_mov_b32_e32 v11, v0
	v_mov_b32_e32 v12, v0
	v_mov_b32_e32 v13, v0
	v_mov_b32_e32 v14, v0
	v_mov_b32_e32 v15, v0
	v_mov_b32_e32 v24, v0
	v_mov_b32_e32 v25, v0
	v_mov_b32_e32 v26, v0
	v_mov_b32_e32 v27, v0
	v_mov_b32_e32 v28, v0
	v_mov_b32_e32 v29, v0
	v_mov_b32_e32 v30, v0
	v_mov_b32_e32 v31, v0
	v_mov_b32_e32 v40, v0
	v_mov_b32_e32 v41, v0
	v_mov_b32_e32 v42, v0
	v_mov_b32_e32 v43, v0
	v_mov_b32_e32 v44, v0
	v_mov_b32_e32 v45, v0
	v_mov_b32_e32 v46, v0
	v_mov_b32_e32 v47, v0
	v_mov_b32_e32 v56, v0
	v_mov_b32_e32 v57, v0
	v_mov_b32_e32 v58, v0
	v_mov_b32_e32 v59, v0
	v_mov_b32_e32 v60, v0
	v_mov_b32_e32 v61, v0
	v_mov_b32_e32 v62, v0
	v_mov_b32_e32 v63, v0
	v_mov_b32_e32 v64, v0
	v_mov_b32_e32 v65, v0
	v_mov_b32_e32 v66, v0
	v_mov_b32_e32 v67, v0
	v_mov_b32_e32 v68, v0
	v_mov_b32_e32 v69, v0
	v_mov_b32_e32 v70, v0
	v_mov_b32_e32 v71, v0
	v_mov_b32_e32 v80, v0
	v_mov_b32_e32 v81, v0
	v_mov_b32_e32 v82, v0
	v_mov_b32_e32 v83, v0
	v_mov_b32_e32 v84, v0
	v_mov_b32_e32 v85, v0
	v_mov_b32_e32 v86, v0
	v_mov_b32_e32 v87, v0
	v_mov_b32_e32 v96, v0
	v_mov_b32_e32 v97, v0
	v_mov_b32_e32 v98, v0
	v_mov_b32_e32 v99, v0
	v_mov_b32_e32 v100, v0
	v_mov_b32_e32 v101, v0
	v_mov_b32_e32 v102, v0
	v_mov_b32_e32 v103, v0
	v_mov_b32_e32 v112, v0
	v_mov_b32_e32 v113, v0
	v_mov_b32_e32 v114, v0
	v_mov_b32_e32 v115, v0
	v_mov_b32_e32 v116, v0
	v_mov_b32_e32 v117, v0
	v_mov_b32_e32 v118, v0
	v_mov_b32_e32 v119, v0
	v_mov_b32_e32 v72, v0
	v_mov_b32_e32 v73, v0
	v_mov_b32_e32 v74, v0
	v_mov_b32_e32 v75, v0
	v_mov_b32_e32 v76, v0
	v_mov_b32_e32 v77, v0
	v_mov_b32_e32 v78, v0
	v_mov_b32_e32 v79, v0
	v_mov_b32_e32 v88, v0
	v_mov_b32_e32 v89, v0
	v_mov_b32_e32 v90, v0
	v_mov_b32_e32 v91, v0
	v_mov_b32_e32 v92, v0
	v_mov_b32_e32 v93, v0
	v_mov_b32_e32 v94, v0
	v_mov_b32_e32 v95, v0
	v_mov_b32_e32 v104, v0
	v_mov_b32_e32 v105, v0
	v_mov_b32_e32 v106, v0
	v_mov_b32_e32 v107, v0
	v_mov_b32_e32 v108, v0
	v_mov_b32_e32 v109, v0
	v_mov_b32_e32 v110, v0
	v_mov_b32_e32 v111, v0
	v_mov_b32_e32 v120, v0
	v_mov_b32_e32 v121, v0
	v_mov_b32_e32 v122, v0
	v_mov_b32_e32 v123, v0
	v_mov_b32_e32 v124, v0
	v_mov_b32_e32 v125, v0
	v_mov_b32_e32 v126, v0
	v_mov_b32_e32 v127, v0
.LBB0_237:
	ds_read_b128 v[150:153], v147
	ds_read_b128 v[154:157], v147 offset:1024
	ds_read_b128 v[158:161], v147 offset:2048
	ds_read_b128 v[162:165], v147 offset:3072
	ds_read_b128 v[166:169], v148
	ds_read_b128 v[170:173], v148 offset:1024
	ds_read_b128 v[174:177], v148 offset:2048
	ds_read_b128 v[178:181], v148 offset:3072
	s_add_u32 s22, s20, 0xfffc0080
	s_addc_u32 s23, s21, -1
	s_cmp_eq_u32 s48, 12
	s_cselect_b32 s25, s13, s23
	s_cselect_b32 s24, s44, s22
	s_cselect_b32 s23, s11, s47
	s_cselect_b32 s22, s45, s46
	v_lshl_add_u64 v[206:207], s[20:21], 0, v[136:137]
	s_add_i32 m0, s19, 0xc000
	ds_read_b128 v[182:185], v149
	ds_read_b128 v[186:189], v149 offset:1024
	ds_read_b128 v[190:193], v149 offset:2048
	ds_read_b128 v[194:197], v149 offset:3072
	ds_read_b128 v[198:201], v149 offset:4096
	ds_read_b128 v[202:205], v149 offset:5120
	ds_read_b128 v[210:213], v149 offset:6144
	ds_read_b128 v[214:217], v149 offset:7168
	global_load_lds_dwordx4 v[206:207], off
	v_lshl_add_u64 v[206:207], s[20:21], 0, v[138:139]
	s_add_i32 m0, s19, 0xe000
	s_nop 0
	global_load_lds_dwordx4 v[206:207], off
	s_waitcnt vmcnt(8)
	s_waitcnt lgkmcnt(0)
	s_barrier
	s_setprio 1
	s_waitcnt lgkmcnt(0)
	v_mfma_f32_16x16x32_bf16 v[124:127], v[150:153], v[182:185], v[124:127]
	v_mfma_f32_16x16x32_bf16 v[120:123], v[158:161], v[182:185], v[120:123]
	v_mfma_f32_16x16x32_bf16 v[108:111], v[150:153], v[190:193], v[108:111]
	v_mfma_f32_16x16x32_bf16 v[104:107], v[158:161], v[190:193], v[104:107]
	v_mfma_f32_16x16x32_bf16 v[92:95], v[150:153], v[198:201], v[92:95]
	v_mfma_f32_16x16x32_bf16 v[88:91], v[158:161], v[198:201], v[88:91]
	v_mfma_f32_16x16x32_bf16 v[76:79], v[150:153], v[210:213], v[76:79]
	v_mfma_f32_16x16x32_bf16 v[72:75], v[158:161], v[210:213], v[72:75]
	v_mfma_f32_16x16x32_bf16 v[124:127], v[154:157], v[186:189], v[124:127]
	v_mfma_f32_16x16x32_bf16 v[120:123], v[162:165], v[186:189], v[120:123]
	v_mfma_f32_16x16x32_bf16 v[108:111], v[154:157], v[194:197], v[108:111]
	v_mfma_f32_16x16x32_bf16 v[104:107], v[162:165], v[194:197], v[104:107]
	v_mfma_f32_16x16x32_bf16 v[92:95], v[154:157], v[202:205], v[92:95]
	v_mfma_f32_16x16x32_bf16 v[88:91], v[162:165], v[202:205], v[88:91]
	v_mfma_f32_16x16x32_bf16 v[76:79], v[154:157], v[214:217], v[76:79]
	v_mfma_f32_16x16x32_bf16 v[72:75], v[162:165], v[214:217], v[72:75]
	s_setprio 0
	s_setprio 1
	v_mfma_f32_16x16x32_bf16 v[116:119], v[166:169], v[182:185], v[116:119]
	v_mfma_f32_16x16x32_bf16 v[112:115], v[174:177], v[182:185], v[112:115]
	v_mfma_f32_16x16x32_bf16 v[100:103], v[166:169], v[190:193], v[100:103]
	v_mfma_f32_16x16x32_bf16 v[96:99], v[174:177], v[190:193], v[96:99]
	v_mfma_f32_16x16x32_bf16 v[84:87], v[166:169], v[198:201], v[84:87]
	v_mfma_f32_16x16x32_bf16 v[80:83], v[174:177], v[198:201], v[80:83]
	v_mfma_f32_16x16x32_bf16 v[68:71], v[166:169], v[210:213], v[68:71]
	v_mfma_f32_16x16x32_bf16 v[64:67], v[174:177], v[210:213], v[64:67]
	v_mfma_f32_16x16x32_bf16 v[116:119], v[170:173], v[186:189], v[116:119]
	v_mfma_f32_16x16x32_bf16 v[112:115], v[178:181], v[186:189], v[112:115]
	v_mfma_f32_16x16x32_bf16 v[100:103], v[170:173], v[194:197], v[100:103]
	v_mfma_f32_16x16x32_bf16 v[96:99], v[178:181], v[194:197], v[96:99]
	v_mfma_f32_16x16x32_bf16 v[84:87], v[170:173], v[202:205], v[84:87]
	v_mfma_f32_16x16x32_bf16 v[80:83], v[178:181], v[202:205], v[80:83]
	v_mfma_f32_16x16x32_bf16 v[68:71], v[170:173], v[214:217], v[68:71]
	v_mfma_f32_16x16x32_bf16 v[64:67], v[178:181], v[214:217], v[64:67]
	s_setprio 0
	s_barrier
	s_add_i32 s49, s40, s28
	v_lshl_add_u64 v[206:207], s[22:23], 0, v[132:133]
	s_mov_b32 m0, s49
	ds_read_b128 v[182:185], v149 offset:16384
	ds_read_b128 v[186:189], v149 offset:17408
	ds_read_b128 v[190:193], v149 offset:18432
	ds_read_b128 v[194:197], v149 offset:19456
	ds_read_b128 v[198:201], v149 offset:20480
	ds_read_b128 v[202:205], v149 offset:21504
	ds_read_b128 v[210:213], v149 offset:22528
	ds_read_b128 v[214:217], v149 offset:23552
	global_load_lds_dwordx4 v[206:207], off
	s_add_i32 m0, s49, 0x2000
	s_add_u32 s50, s22, 0x40000
	v_lshl_add_u64 v[218:219], s[22:23], 0, v[128:129]
	s_addc_u32 s51, s23, 0
	s_add_i32 s49, s41, s28
	global_load_lds_dwordx4 v[218:219], off
	v_lshl_add_u64 v[220:221], s[50:51], 0, v[132:133]
	s_mov_b32 m0, s49
	v_lshl_add_u64 v[222:223], s[24:25], 0, v[130:131]
	global_load_lds_dwordx4 v[220:221], off
	v_lshl_add_u64 v[220:221], s[50:51], 0, v[128:129]
	s_add_i32 m0, s49, 0x2000
	s_nop 0
	global_load_lds_dwordx4 v[220:221], off
	v_lshl_add_u64 v[220:221], s[24:25], 0, v[134:135]
	s_mov_b32 m0, s19
	s_nop 0
	global_load_lds_dwordx4 v[220:221], off
	s_mov_b32 m0, s31
	s_nop 0
	global_load_lds_dwordx4 v[222:223], off
	s_waitcnt vmcnt(8)
	s_waitcnt lgkmcnt(0)
	s_barrier
	s_setprio 1
	s_waitcnt lgkmcnt(0)
	v_mfma_f32_16x16x32_bf16 v[60:63], v[150:153], v[182:185], v[60:63]
	v_mfma_f32_16x16x32_bf16 v[56:59], v[158:161], v[182:185], v[56:59]
	v_mfma_f32_16x16x32_bf16 v[44:47], v[150:153], v[190:193], v[44:47]
	v_mfma_f32_16x16x32_bf16 v[40:43], v[158:161], v[190:193], v[40:43]
	v_mfma_f32_16x16x32_bf16 v[28:31], v[150:153], v[198:201], v[28:31]
	v_mfma_f32_16x16x32_bf16 v[24:27], v[158:161], v[198:201], v[24:27]
	v_mfma_f32_16x16x32_bf16 v[12:15], v[150:153], v[210:213], v[12:15]
	v_mfma_f32_16x16x32_bf16 v[8:11], v[158:161], v[210:213], v[8:11]
	v_mfma_f32_16x16x32_bf16 v[60:63], v[154:157], v[186:189], v[60:63]
	v_mfma_f32_16x16x32_bf16 v[56:59], v[162:165], v[186:189], v[56:59]
	v_mfma_f32_16x16x32_bf16 v[44:47], v[154:157], v[194:197], v[44:47]
	v_mfma_f32_16x16x32_bf16 v[40:43], v[162:165], v[194:197], v[40:43]
	v_mfma_f32_16x16x32_bf16 v[28:31], v[154:157], v[202:205], v[28:31]
	v_mfma_f32_16x16x32_bf16 v[24:27], v[162:165], v[202:205], v[24:27]
	v_mfma_f32_16x16x32_bf16 v[12:15], v[154:157], v[214:217], v[12:15]
	v_mfma_f32_16x16x32_bf16 v[8:11], v[162:165], v[214:217], v[8:11]
	s_setprio 0
	s_setprio 1
	v_mfma_f32_16x16x32_bf16 v[52:55], v[166:169], v[182:185], v[52:55]
	v_mfma_f32_16x16x32_bf16 v[48:51], v[174:177], v[182:185], v[48:51]
	v_mfma_f32_16x16x32_bf16 v[36:39], v[166:169], v[190:193], v[36:39]
	v_mfma_f32_16x16x32_bf16 v[32:35], v[174:177], v[190:193], v[32:35]
	v_mfma_f32_16x16x32_bf16 v[20:23], v[166:169], v[198:201], v[20:23]
	v_mfma_f32_16x16x32_bf16 v[16:19], v[174:177], v[198:201], v[16:19]
	v_mfma_f32_16x16x32_bf16 v[4:7], v[166:169], v[210:213], v[4:7]
	v_mfma_f32_16x16x32_bf16 v[0:3], v[174:177], v[210:213], v[0:3]
	v_mfma_f32_16x16x32_bf16 v[52:55], v[170:173], v[186:189], v[52:55]
	v_mfma_f32_16x16x32_bf16 v[48:51], v[178:181], v[186:189], v[48:51]
	v_mfma_f32_16x16x32_bf16 v[36:39], v[170:173], v[194:197], v[36:39]
	v_mfma_f32_16x16x32_bf16 v[32:35], v[178:181], v[194:197], v[32:35]
	v_mfma_f32_16x16x32_bf16 v[20:23], v[170:173], v[202:205], v[20:23]
	v_mfma_f32_16x16x32_bf16 v[16:19], v[178:181], v[202:205], v[16:19]
	v_mfma_f32_16x16x32_bf16 v[4:7], v[170:173], v[214:217], v[4:7]
	v_mfma_f32_16x16x32_bf16 v[0:3], v[178:181], v[214:217], v[0:3]
	s_setprio 0
	s_barrier
	s_add_i32 s49, 0, 0x18000
	s_add_i32 s50, 0, 0x1c000
	v_add_u32_e32 v162, s49, v145
	v_add_u32_e32 v178, s50, v145
	ds_read_b128 v[150:153], v162
	ds_read_b128 v[154:157], v162 offset:1024
	ds_read_b128 v[158:161], v162 offset:2048
	ds_read_b128 v[162:165], v162 offset:3072
	ds_read_b128 v[166:169], v178
	ds_read_b128 v[170:173], v178 offset:1024
	ds_read_b128 v[174:177], v178 offset:2048
	ds_read_b128 v[178:181], v178 offset:3072
	s_add_u32 s24, s24, 0x40000
	s_addc_u32 s25, s25, 0
	s_mov_b32 m0, s33
	v_lshl_add_u64 v[224:225], s[24:25], 0, v[134:135]
	ds_read_b128 v[182:185], v149 offset:32768
	ds_read_b128 v[186:189], v149 offset:33792
	ds_read_b128 v[190:193], v149 offset:34816
	ds_read_b128 v[194:197], v149 offset:35840
	ds_read_b128 v[198:201], v149 offset:36864
	ds_read_b128 v[202:205], v149 offset:37888
	ds_read_b128 v[210:213], v149 offset:38912
	ds_read_b128 v[214:217], v149 offset:39936
	global_load_lds_dwordx4 v[224:225], off
	v_lshl_add_u64 v[224:225], s[24:25], 0, v[130:131]
	s_mov_b32 m0, s34
	s_nop 0
	global_load_lds_dwordx4 v[224:225], off
	s_waitcnt vmcnt(8)
	s_waitcnt lgkmcnt(0)
	s_barrier
	s_setprio 1
	s_waitcnt lgkmcnt(0)
	v_mfma_f32_16x16x32_bf16 v[124:127], v[150:153], v[182:185], v[124:127]
	v_mfma_f32_16x16x32_bf16 v[120:123], v[158:161], v[182:185], v[120:123]
	v_mfma_f32_16x16x32_bf16 v[108:111], v[150:153], v[190:193], v[108:111]
	v_mfma_f32_16x16x32_bf16 v[104:107], v[158:161], v[190:193], v[104:107]
	v_mfma_f32_16x16x32_bf16 v[92:95], v[150:153], v[198:201], v[92:95]
	v_mfma_f32_16x16x32_bf16 v[88:91], v[158:161], v[198:201], v[88:91]
	v_mfma_f32_16x16x32_bf16 v[76:79], v[150:153], v[210:213], v[76:79]
	v_mfma_f32_16x16x32_bf16 v[72:75], v[158:161], v[210:213], v[72:75]
	v_mfma_f32_16x16x32_bf16 v[124:127], v[154:157], v[186:189], v[124:127]
	v_mfma_f32_16x16x32_bf16 v[120:123], v[162:165], v[186:189], v[120:123]
	v_mfma_f32_16x16x32_bf16 v[108:111], v[154:157], v[194:197], v[108:111]
	v_mfma_f32_16x16x32_bf16 v[104:107], v[162:165], v[194:197], v[104:107]
	v_mfma_f32_16x16x32_bf16 v[92:95], v[154:157], v[202:205], v[92:95]
	v_mfma_f32_16x16x32_bf16 v[88:91], v[162:165], v[202:205], v[88:91]
	v_mfma_f32_16x16x32_bf16 v[76:79], v[154:157], v[214:217], v[76:79]
	v_mfma_f32_16x16x32_bf16 v[72:75], v[162:165], v[214:217], v[72:75]
	s_setprio 0
	s_setprio 1
	v_mfma_f32_16x16x32_bf16 v[116:119], v[166:169], v[182:185], v[116:119]
	v_mfma_f32_16x16x32_bf16 v[112:115], v[174:177], v[182:185], v[112:115]
	v_mfma_f32_16x16x32_bf16 v[100:103], v[166:169], v[190:193], v[100:103]
	v_mfma_f32_16x16x32_bf16 v[96:99], v[174:177], v[190:193], v[96:99]
	v_mfma_f32_16x16x32_bf16 v[84:87], v[166:169], v[198:201], v[84:87]
	v_mfma_f32_16x16x32_bf16 v[80:83], v[174:177], v[198:201], v[80:83]
	v_mfma_f32_16x16x32_bf16 v[68:71], v[166:169], v[210:213], v[68:71]
	v_mfma_f32_16x16x32_bf16 v[64:67], v[174:177], v[210:213], v[64:67]
	v_mfma_f32_16x16x32_bf16 v[116:119], v[170:173], v[186:189], v[116:119]
	v_mfma_f32_16x16x32_bf16 v[112:115], v[178:181], v[186:189], v[112:115]
	v_mfma_f32_16x16x32_bf16 v[100:103], v[170:173], v[194:197], v[100:103]
	v_mfma_f32_16x16x32_bf16 v[96:99], v[178:181], v[194:197], v[96:99]
	v_mfma_f32_16x16x32_bf16 v[84:87], v[170:173], v[202:205], v[84:87]
	v_mfma_f32_16x16x32_bf16 v[80:83], v[178:181], v[202:205], v[80:83]
	v_mfma_f32_16x16x32_bf16 v[68:71], v[170:173], v[214:217], v[68:71]
	v_mfma_f32_16x16x32_bf16 v[64:67], v[178:181], v[214:217], v[64:67]
	s_setprio 0
	s_barrier
	s_add_i32 s24, s49, s28
	v_lshl_add_u64 v[206:207], v[206:207], 0, s[6:7]
	s_mov_b32 m0, s24
	ds_read_b128 v[182:185], v149 offset:49152
	ds_read_b128 v[186:189], v149 offset:50176
	ds_read_b128 v[190:193], v149 offset:51200
	ds_read_b128 v[194:197], v149 offset:52224
	ds_read_b128 v[198:201], v149 offset:53248
	ds_read_b128 v[202:205], v149 offset:54272
	ds_read_b128 v[210:213], v149 offset:55296
	ds_read_b128 v[214:217], v149 offset:56320
	global_load_lds_dwordx4 v[206:207], off
	s_add_i32 m0, s24, 0x2000
	s_add_u32 s22, s22, 0x40080
	v_lshl_add_u64 v[206:207], v[218:219], 0, s[6:7]
	s_addc_u32 s23, s23, 0
	s_add_i32 s24, s50, s28
	global_load_lds_dwordx4 v[206:207], off
	v_lshl_add_u64 v[206:207], s[22:23], 0, v[132:133]
	s_mov_b32 m0, s24
	s_nop 0
	global_load_lds_dwordx4 v[206:207], off
	v_lshl_add_u64 v[206:207], s[22:23], 0, v[128:129]
	s_add_i32 m0, s24, 0x2000
	s_nop 0
	global_load_lds_dwordx4 v[206:207], off
	v_lshl_add_u64 v[206:207], v[220:221], 0, s[6:7]
	s_mov_b32 m0, s36
	s_nop 0
	global_load_lds_dwordx4 v[206:207], off
	v_lshl_add_u64 v[206:207], v[222:223], 0, s[6:7]
	s_mov_b32 m0, s37
	s_nop 0
	global_load_lds_dwordx4 v[206:207], off
	s_waitcnt vmcnt(8)
	s_waitcnt lgkmcnt(0)
	s_barrier
	s_setprio 1
	s_waitcnt lgkmcnt(0)
	v_mfma_f32_16x16x32_bf16 v[60:63], v[150:153], v[182:185], v[60:63]
	v_mfma_f32_16x16x32_bf16 v[56:59], v[158:161], v[182:185], v[56:59]
	v_mfma_f32_16x16x32_bf16 v[44:47], v[150:153], v[190:193], v[44:47]
	v_mfma_f32_16x16x32_bf16 v[40:43], v[158:161], v[190:193], v[40:43]
	v_mfma_f32_16x16x32_bf16 v[28:31], v[150:153], v[198:201], v[28:31]
	v_mfma_f32_16x16x32_bf16 v[24:27], v[158:161], v[198:201], v[24:27]
	v_mfma_f32_16x16x32_bf16 v[12:15], v[150:153], v[210:213], v[12:15]
	v_mfma_f32_16x16x32_bf16 v[8:11], v[158:161], v[210:213], v[8:11]
	v_mfma_f32_16x16x32_bf16 v[60:63], v[154:157], v[186:189], v[60:63]
	v_mfma_f32_16x16x32_bf16 v[56:59], v[162:165], v[186:189], v[56:59]
	v_mfma_f32_16x16x32_bf16 v[44:47], v[154:157], v[194:197], v[44:47]
	v_mfma_f32_16x16x32_bf16 v[40:43], v[162:165], v[194:197], v[40:43]
	v_mfma_f32_16x16x32_bf16 v[28:31], v[154:157], v[202:205], v[28:31]
	v_mfma_f32_16x16x32_bf16 v[24:27], v[162:165], v[202:205], v[24:27]
	v_mfma_f32_16x16x32_bf16 v[12:15], v[154:157], v[214:217], v[12:15]
	v_mfma_f32_16x16x32_bf16 v[8:11], v[162:165], v[214:217], v[8:11]
	s_setprio 0
	s_setprio 1
	v_mfma_f32_16x16x32_bf16 v[52:55], v[166:169], v[182:185], v[52:55]
	v_mfma_f32_16x16x32_bf16 v[48:51], v[174:177], v[182:185], v[48:51]
	v_mfma_f32_16x16x32_bf16 v[36:39], v[166:169], v[190:193], v[36:39]
	v_mfma_f32_16x16x32_bf16 v[32:35], v[174:177], v[190:193], v[32:35]
	v_mfma_f32_16x16x32_bf16 v[20:23], v[166:169], v[198:201], v[20:23]
	v_mfma_f32_16x16x32_bf16 v[16:19], v[174:177], v[198:201], v[16:19]
	v_mfma_f32_16x16x32_bf16 v[4:7], v[166:169], v[210:213], v[4:7]
	v_mfma_f32_16x16x32_bf16 v[0:3], v[174:177], v[210:213], v[0:3]
	v_mfma_f32_16x16x32_bf16 v[52:55], v[170:173], v[186:189], v[52:55]
	v_mfma_f32_16x16x32_bf16 v[48:51], v[178:181], v[186:189], v[48:51]
	v_mfma_f32_16x16x32_bf16 v[36:39], v[170:173], v[194:197], v[36:39]
	v_mfma_f32_16x16x32_bf16 v[32:35], v[178:181], v[194:197], v[32:35]
	v_mfma_f32_16x16x32_bf16 v[20:23], v[170:173], v[202:205], v[20:23]
	v_mfma_f32_16x16x32_bf16 v[16:19], v[178:181], v[202:205], v[16:19]
	v_mfma_f32_16x16x32_bf16 v[4:7], v[170:173], v[214:217], v[4:7]
	v_mfma_f32_16x16x32_bf16 v[0:3], v[178:181], v[214:217], v[0:3]
	s_setprio 0
	s_barrier
	s_add_i32 s48, s48, 2
	s_add_u32 s20, s20, 0x100
	s_addc_u32 s21, s21, 0
	s_add_u32 s46, s46, 0x100
	s_addc_u32 s47, s47, 0
	s_cmp_gt_u32 s48, 13
	s_cbranch_scc0 .LBB0_237
	s_and_b64 vcc, exec, s[8:9]
	s_cbranch_vccz .LBB0_240
	s_barrier
